# GEMM epilogue: mode-specific descriptor readfirstlanes moved into their mode blocks (12 and 7 fewer per tile on the common path); scheduler mask inversion done on the SALU
# baseline (speedup 1.0000x reference)
;     DI bool next(int i, Unit& u) const {
;         const long L = (long)i * G + c; if (L >= nwg) return false;
;         int wgid = (int)L; { const int q = nwg / NXCD, r = nwg % NXCD, xcd = wgid % NXCD, off = wgid / NXCD; wgid = (xcd < r ? xcd * (q + 1) : r * (q + 1) + (xcd - r) * q) + off; }
;         if ((nM & (WGM - 1)) == 0) {
;             const int t = wgid >> 3, gid = (int)(((float)t + 0.5f) * invN);
;             u.pm = gid * WGM + (wgid & (WGM - 1)); u.pn = t - gid * nN; return true; }
;         const int nig = WGM * nN, gid = wgid / nig, fm = gid * WGM, gsz = (nM - fm) < WGM ? (nM - fm) : WGM;
;         u.pm = fm + ((wgid % nig) % gsz); u.pn = (wgid % nig) / gsz; return true;
; DI void gemm_phase(LAS unsigned char* lds, const Gemm g, const StaticOrder& S, const bool eperm) {
;     ...
;         const bool has_next = S.next(ui + 1, nxt);
;         const char* nA = has_next ? (const char*)g.A + (size_t)nxt.pm * tstepA : cA; const char* nB = has_next ? (const char*)g.Bt + (size_t)nxt.pn * tstepB : cB;
.LBB0_787:
	s_andn2_b64 s[4:5], exec, s[6:7]
	s_andn2_b64 vcc, exec, s[6:7]
	s_mov_b64 s[26:27], s[34:35]
	s_cbranch_vccnz .LBB0_789
	s_ashr_i32 s0, s63, 31
	s_mul_hi_u32 s1, s12, s63
	s_mul_i32 s0, s12, s0
	s_add_i32 s0, s1, s0
	s_mul_i32 s1, s13, s63
	s_add_i32 s0, s0, s1
	s_mul_i32 s1, s12, s63
	s_add_u32 s26, s60, s1
	s_addc_u32 s27, s84, s0

; #define GAS __attribute__((address_space(1)))
;     DI void operator()(const f32x4 (&acc)[2][2][4][2], const Unit& u, int wr, int wc, int fr, int fq) const {
;     ...
;             const int rowt = row_off + u.pm * BM; const bool lat = rowt < MLAT;
;             const int vec = lat ? (rowt >> 13) : 8;
;             const float* bp = lat ? base_lat : base_ctx - (size_t)MLAT * DM; float* op = lat ? out_lat : out_ctx - (size_t)MLAT * DM;
;             const float* mrow = modp + (size_t)vec * 9216 + gate_chunk * 1024;
;             const int col0 = u.pn * BM + wc * 64 + 4 * fq;
;             f32x4 gv[2][2];
; #pragma unroll
;             for (int bj = 0; bj < 2; ++bj)
; #pragma unroll
;                 for (int n = 0; n < 2; ++n) gv[bj][n] = *(const GAS f32x4*)(mrow + col0 + bj * 32 + n * 16) * gs;
; DI Epi epi_load(LAS unsigned char* lds) {
;     ...
;     for (int i = 0; i < 7; ++i) { w[4 * i] = __builtin_amdgcn_readfirstlane(q[i].x); w[4 * i + 1] = __builtin_amdgcn_readfirstlane(q[i].y); w[4 * i + 2] = __builtin_amdgcn_readfirstlane(q[i].z); w[4 * i + 3] = __builtin_amdgcn_readfirstlane(q[i].w); }
;     ...
;     Epi e;
;     e.mode = (int)w[0]; e.perm = w[1] != 0u; e.ldc = (int)w[2]; e.gate_chunk = (int)w[3]; e.gi = (int)w[4]; e.gs = __uint_as_float(w[5]);
;     e.O = (bf16_t*)W64(6); e.base_lat = (const float*)W64(8); e.base_ctx = (const float*)W64(10); e.out_lat = (float*)W64(12); e.out_ctx = (float*)W64(14);
;     e.modp = (const float*)W64(16); e.bias = (const float*)W64(18); e.BR = (bf16_t*)W64(20); e.MG = (bf16_t*)W64(22); e.row_off = (int)w[24];
.LBB0_796:
	v_readlane_b32 s0, v252, 38
	s_lshl_b32 s1, s41, 8
	s_mov_b64 s[82:83], -1
	v_mov_b32_e32 v158, s0
	v_mov_b32_e32 v159, s75
	v_mov_b32_e32 v160, s90
	v_mov_b32_e32 v161, s91
	v_mov_b32_e32 v162, s48
	v_mov_b32_e32 v163, s49
	v_mov_b32_e32 v164, s64
	ds_read_b128 v[130:133], v158
	ds_read_b128 v[134:137], v159
	ds_read_b128 v[138:141], v160
	ds_read_b128 v[142:145], v161
	ds_read_b128 v[146:149], v162
	ds_read_b128 v[150:153], v163
	ds_read_b128 v[154:157], v164
	s_waitcnt lgkmcnt(0)
	v_readfirstlane_b32 s55, v130
	v_readfirstlane_b32 s50, v132
	s_waitcnt lgkmcnt(0)
	v_readfirstlane_b32 s0, v154
	s_add_i32 s41, s0, s1
	v_readfirstlane_b32 s30, v136
	v_readfirstlane_b32 s31, v137
	v_add_u32_e32 v176, s41, v183
	s_mov_b64 s[0:1], 0
	s_cmp_lt_i32 s55, 1
	s_mov_b64 s[6:7], 0
	s_cbranch_scc1 .LBB0_801
	s_cmp_gt_i32 s55, 1
	s_cbranch_scc0 .LBB0_808
	s_cmp_eq_u32 s55, 2
	s_mov_b64 s[6:7], -1
	s_cbranch_scc0 .LBB0_800
	v_readfirstlane_b32 s33, v133
	v_readfirstlane_b32 s40, v135
	v_readfirstlane_b32 vcc_lo, v138
	v_readfirstlane_b32 vcc_hi, v139
	v_readfirstlane_b32 s58, v140
	v_readfirstlane_b32 s56, v141
	v_readfirstlane_b32 s72, v142
	v_readfirstlane_b32 s3, v143
	v_readfirstlane_b32 s57, v144
	v_readfirstlane_b32 s74, v145
	v_readfirstlane_b32 s76, v146
	v_readfirstlane_b32 s77, v147
	s_min_i32 s6, s41, 0x10000
	s_ashr_i32 s6, s6, 13
	s_add_u32 s58, s58, 0xf0000000
	s_addc_u32 s56, s56, -1
	s_add_u32 s57, s57, 0xf0000000
	s_addc_u32 s74, s74, -1
	v_mul_hi_i32_i24_e32 v131, s6, v235
	v_mul_i32_i24_e32 v130, s6, v235
	s_lshl_b32 s6, s33, 10
	s_ashr_i32 s7, s6, 31
	v_lshl_add_u64 v[130:131], s[76:77], 0, v[130:131]
	s_lshl_b64 s[6:7], s[6:7], 2
	v_lshl_or_b32 v150, s51, 8, v185
	v_lshl_add_u64 v[130:131], v[130:131], 0, s[6:7]
	v_ashrrev_i32_e32 v151, 31, v150
	v_lshl_add_u64 v[164:165], v[150:151], 2, v[130:131]
	global_load_dwordx4 v[130:133], v[164:165], off
	global_load_dwordx4 v[134:137], v[164:165], off offset:64
	global_load_dwordx4 v[138:141], v[164:165], off offset:128
	global_load_dwordx4 v[142:145], v[164:165], off offset:192
	v_ashrrev_i32_e32 v177, 31, v176
	s_cmp_lt_i32 s41, 0x10000
	s_cselect_b32 s7, s3, s74
	s_cselect_b32 s6, s72, s57
	s_cselect_b32 vcc_hi, vcc_hi, s56
	s_cselect_b32 vcc_lo, vcc_lo, s58
	v_lshlrev_b64 v[146:147], 10, v[176:177]
	v_lshl_add_u64 v[146:147], v[146:147], 0, v[150:151]
	v_lshlrev_b64 v[146:147], 2, v[146:147]
	v_lshl_add_u64 v[178:179], vcc, 0, v[146:147]
	v_lshl_add_u64 v[180:181], s[6:7], 0, v[146:147]
	global_load_dwordx4 v[148:151], v[178:179], off
	global_load_dwordx4 v[152:155], v[178:179], off offset:64
	global_load_dwordx4 v[156:159], v[178:179], off offset:128
	global_load_dwordx4 v[160:163], v[178:179], off offset:192
	s_mov_b64 s[56:57], 0x10000
	v_lshl_add_u64 v[146:147], v[178:179], 0, s[56:57]
	v_lshl_add_u64 v[190:191], v[180:181], 0, s[56:57]
	global_load_dwordx4 v[236:239], v[146:147], off
	global_load_dwordx4 v[240:243], v[146:147], off offset:64
	global_load_dwordx4 v[244:247], v[146:147], off offset:128
	global_load_dwordx4 v[248:251], v[146:147], off offset:192
	s_mov_b64 s[56:57], 0x20000
	v_lshl_add_u64 v[146:147], v[178:179], 0, s[56:57]
	v_lshl_add_u64 v[208:209], v[180:181], 0, s[56:57]
	global_load_dwordx4 v[194:197], v[146:147], off
	global_load_dwordx4 v[200:203], v[146:147], off offset:64
	global_load_dwordx4 v[204:207], v[146:147], off offset:128
	global_load_dwordx4 v[230:233], v[146:147], off offset:192
	s_waitcnt vmcnt(12)
	v_pk_mul_f32 v[130:131], v[130:131], s[40:41] op_sel_hi:[1,0]
	v_pk_mul_f32 v[132:133], v[132:133], s[40:41] op_sel_hi:[1,0]
	v_pk_mul_f32 v[134:135], v[134:135], s[40:41] op_sel_hi:[1,0]
	v_pk_mul_f32 v[136:137], v[136:137], s[40:41] op_sel_hi:[1,0]
	v_pk_mul_f32 v[138:139], v[138:139], s[40:41] op_sel_hi:[1,0]
	v_pk_mul_f32 v[140:141], v[140:141], s[40:41] op_sel_hi:[1,0]
	v_pk_mul_f32 v[142:143], v[142:143], s[40:41] op_sel_hi:[1,0]
	v_pk_mul_f32 v[144:145], v[144:145], s[40:41] op_sel_hi:[1,0]
	s_waitcnt vmcnt(8)
	v_pk_fma_f32 v[148:149], v[122:123], v[130:131], v[148:149]
	v_pk_fma_f32 v[150:151], v[124:125], v[132:133], v[150:151]
	v_pk_fma_f32 v[152:153], v[126:127], v[134:135], v[152:153]
	v_pk_fma_f32 v[154:155], v[128:129], v[136:137], v[154:155]
	v_pk_fma_f32 v[156:157], v[118:119], v[138:139], v[156:157]
	v_pk_fma_f32 v[158:159], v[120:121], v[140:141], v[158:159]
	v_pk_fma_f32 v[160:161], v[114:115], v[142:143], v[160:161]
	v_pk_fma_f32 v[162:163], v[116:117], v[144:145], v[162:163]
	global_store_dwordx4 v[180:181], v[148:151], off
	global_store_dwordx4 v[180:181], v[152:155], off offset:64
	global_store_dwordx4 v[180:181], v[156:159], off offset:128
	global_store_dwordx4 v[180:181], v[160:163], off offset:192
	s_mov_b64 s[56:57], 0x30000
	v_lshl_add_u64 v[146:147], v[178:179], 0, s[56:57]
	v_lshl_add_u64 v[164:165], v[180:181], 0, s[56:57]
	global_load_dwordx4 v[148:151], v[146:147], off
	global_load_dwordx4 v[152:155], v[146:147], off offset:64
	global_load_dwordx4 v[156:159], v[146:147], off offset:128
	global_load_dwordx4 v[160:163], v[146:147], off offset:192
	s_waitcnt vmcnt(12)
; #define GAS __attribute__((address_space(1)))
;     DI void operator()(const f32x4 (&acc)[2][2][4][2], const Unit& u, int wr, int wc, int fr, int fq) const {
;     ...
; #pragma unroll
;             for (int ai = 0; ai < 2; ++ai)
; #pragma unroll
;                 for (int m = 0; m < 4; ++m) { const size_t off = (size_t)(row0 + ai * HALF + m * 16) * DM + col0; f32x4 b[2][2];
; #pragma unroll
;                     for (int bj = 0; bj < 2; ++bj)
; #pragma unroll
;                         for (int n = 0; n < 2; ++n) b[bj][n] = *(const GAS f32x4*)(bp + off + bj * 32 + n * 16);
; #pragma unroll
;                     for (int bj = 0; bj < 2; ++bj)
; #pragma unroll
;                         for (int n = 0; n < 2; ++n) *(GAS f32x4*)(op + off + bj * 32 + n * 16) = b[bj][n] + gv[bj][n] * acc[ai][bj][m][n]; }
	v_pk_fma_f32 v[236:237], v[110:111], v[130:131], v[236:237]
	v_pk_fma_f32 v[238:239], v[112:113], v[132:133], v[238:239]
	v_pk_fma_f32 v[240:241], v[106:107], v[134:135], v[240:241]
	v_pk_fma_f32 v[242:243], v[108:109], v[136:137], v[242:243]
	v_pk_fma_f32 v[244:245], v[102:103], v[138:139], v[244:245]
	v_pk_fma_f32 v[246:247], v[104:105], v[140:141], v[246:247]
	v_pk_fma_f32 v[248:249], v[98:99], v[142:143], v[248:249]
	v_pk_fma_f32 v[250:251], v[100:101], v[144:145], v[250:251]
	global_store_dwordx4 v[190:191], v[236:239], off
	global_store_dwordx4 v[190:191], v[240:243], off offset:64
	global_store_dwordx4 v[190:191], v[244:247], off offset:128
	global_store_dwordx4 v[190:191], v[248:251], off offset:192
	s_mov_b64 s[56:57], 0x80000
	v_lshl_add_u64 v[146:147], v[178:179], 0, s[56:57]
	v_lshl_add_u64 v[190:191], v[180:181], 0, s[56:57]
	global_load_dwordx4 v[236:239], v[146:147], off
	global_load_dwordx4 v[240:243], v[146:147], off offset:64
	global_load_dwordx4 v[244:247], v[146:147], off offset:128
	global_load_dwordx4 v[248:251], v[146:147], off offset:192
	s_waitcnt vmcnt(16)
	v_pk_fma_f32 v[194:195], v[94:95], v[130:131], v[194:195]
	v_pk_fma_f32 v[196:197], v[96:97], v[132:133], v[196:197]
	v_pk_fma_f32 v[200:201], v[90:91], v[134:135], v[200:201]
	v_pk_fma_f32 v[202:203], v[92:93], v[136:137], v[202:203]
	v_pk_fma_f32 v[204:205], v[86:87], v[138:139], v[204:205]
	v_pk_fma_f32 v[206:207], v[88:89], v[140:141], v[206:207]
	v_pk_fma_f32 v[230:231], v[82:83], v[142:143], v[230:231]
	v_pk_fma_f32 v[232:233], v[84:85], v[144:145], v[232:233]
	global_store_dwordx4 v[208:209], v[194:197], off
	global_store_dwordx4 v[208:209], v[200:203], off offset:64
	global_store_dwordx4 v[208:209], v[204:207], off offset:128
	global_store_dwordx4 v[208:209], v[230:233], off offset:192
	s_mov_b64 s[56:57], 0x90000
	v_lshl_add_u64 v[146:147], v[178:179], 0, s[56:57]
	v_lshl_add_u64 v[208:209], v[180:181], 0, s[56:57]
	global_load_dwordx4 v[194:197], v[146:147], off
	global_load_dwordx4 v[200:203], v[146:147], off offset:64
	global_load_dwordx4 v[204:207], v[146:147], off offset:128
	global_load_dwordx4 v[230:233], v[146:147], off offset:192
	s_waitcnt vmcnt(16)
	v_pk_fma_f32 v[148:149], v[78:79], v[130:131], v[148:149]
	v_pk_fma_f32 v[150:151], v[80:81], v[132:133], v[150:151]
	v_pk_fma_f32 v[152:153], v[74:75], v[134:135], v[152:153]
	v_pk_fma_f32 v[154:155], v[76:77], v[136:137], v[154:155]
	v_pk_fma_f32 v[156:157], v[70:71], v[138:139], v[156:157]
	v_pk_fma_f32 v[158:159], v[72:73], v[140:141], v[158:159]
	v_pk_fma_f32 v[160:161], v[66:67], v[142:143], v[160:161]
	v_pk_fma_f32 v[162:163], v[68:69], v[144:145], v[162:163]
	global_store_dwordx4 v[164:165], v[148:151], off
	global_store_dwordx4 v[164:165], v[152:155], off offset:64
	global_store_dwordx4 v[164:165], v[156:159], off offset:128
	global_store_dwordx4 v[164:165], v[160:163], off offset:192
	s_mov_b64 s[56:57], 0xa0000
	v_lshl_add_u64 v[146:147], v[178:179], 0, s[56:57]
	v_lshl_add_u64 v[164:165], v[180:181], 0, s[56:57]
	global_load_dwordx4 v[148:151], v[146:147], off
	global_load_dwordx4 v[152:155], v[146:147], off offset:64
	global_load_dwordx4 v[156:159], v[146:147], off offset:128
	global_load_dwordx4 v[160:163], v[146:147], off offset:192
	s_waitcnt vmcnt(16)
	v_pk_fma_f32 v[236:237], v[62:63], v[130:131], v[236:237]
	v_pk_fma_f32 v[238:239], v[64:65], v[132:133], v[238:239]
	v_pk_fma_f32 v[240:241], v[58:59], v[134:135], v[240:241]
	v_pk_fma_f32 v[242:243], v[60:61], v[136:137], v[242:243]
	v_pk_fma_f32 v[244:245], v[54:55], v[138:139], v[244:245]
	v_pk_fma_f32 v[246:247], v[56:57], v[140:141], v[246:247]
	v_pk_fma_f32 v[248:249], v[50:51], v[142:143], v[248:249]
	v_pk_fma_f32 v[250:251], v[52:53], v[144:145], v[250:251]
	global_store_dwordx4 v[190:191], v[236:239], off
	global_store_dwordx4 v[190:191], v[240:243], off offset:64
	global_store_dwordx4 v[190:191], v[244:247], off offset:128
	global_store_dwordx4 v[190:191], v[248:251], off offset:192
	s_mov_b64 s[56:57], 0xb0000
	v_lshl_add_u64 v[146:147], v[178:179], 0, s[56:57]
	v_lshl_add_u64 v[190:191], v[180:181], 0, s[56:57]
	global_load_dwordx4 v[236:239], v[146:147], off
	global_load_dwordx4 v[240:243], v[146:147], off offset:64
	global_load_dwordx4 v[244:247], v[146:147], off offset:128
	global_load_dwordx4 v[248:251], v[146:147], off offset:192
	s_waitcnt vmcnt(16)
	v_pk_fma_f32 v[194:195], v[46:47], v[130:131], v[194:195]
	v_pk_fma_f32 v[196:197], v[48:49], v[132:133], v[196:197]
	v_pk_fma_f32 v[200:201], v[42:43], v[134:135], v[200:201]
	v_pk_fma_f32 v[202:203], v[44:45], v[136:137], v[202:203]
	v_pk_fma_f32 v[204:205], v[38:39], v[138:139], v[204:205]
	v_pk_fma_f32 v[206:207], v[40:41], v[140:141], v[206:207]
	v_pk_fma_f32 v[230:231], v[34:35], v[142:143], v[230:231]
	v_pk_fma_f32 v[232:233], v[36:37], v[144:145], v[232:233]
	global_store_dwordx4 v[208:209], v[194:197], off
	global_store_dwordx4 v[208:209], v[200:203], off offset:64
	global_store_dwordx4 v[208:209], v[204:207], off offset:128
	global_store_dwordx4 v[208:209], v[230:233], off offset:192
	s_waitcnt vmcnt(12)
	v_pk_fma_f32 v[148:149], v[30:31], v[130:131], v[148:149]
	v_pk_fma_f32 v[150:151], v[32:33], v[132:133], v[150:151]
	v_pk_fma_f32 v[152:153], v[26:27], v[134:135], v[152:153]
	v_pk_fma_f32 v[154:155], v[28:29], v[136:137], v[154:155]
	v_pk_fma_f32 v[156:157], v[22:23], v[138:139], v[156:157]
	v_pk_fma_f32 v[158:159], v[24:25], v[140:141], v[158:159]
	v_pk_fma_f32 v[160:161], v[18:19], v[142:143], v[160:161]
	v_pk_fma_f32 v[162:163], v[20:21], v[144:145], v[162:163]
	global_store_dwordx4 v[164:165], v[148:151], off
	global_store_dwordx4 v[164:165], v[152:155], off offset:64
	global_store_dwordx4 v[164:165], v[156:159], off offset:128
	global_store_dwordx4 v[164:165], v[160:163], off offset:192
	s_waitcnt vmcnt(8)
	v_pk_fma_f32 v[236:237], v[14:15], v[130:131], v[236:237]
	v_pk_fma_f32 v[238:239], v[16:17], v[132:133], v[238:239]
	v_pk_fma_f32 v[240:241], v[10:11], v[134:135], v[240:241]
	v_pk_fma_f32 v[242:243], v[12:13], v[136:137], v[242:243]
	v_pk_fma_f32 v[244:245], v[6:7], v[138:139], v[244:245]
	v_pk_fma_f32 v[246:247], v[8:9], v[140:141], v[246:247]
	v_pk_fma_f32 v[248:249], v[2:3], v[142:143], v[248:249]
	v_pk_fma_f32 v[250:251], v[4:5], v[144:145], v[250:251]
	global_store_dwordx4 v[190:191], v[236:239], off
	global_store_dwordx4 v[190:191], v[240:243], off offset:64
	global_store_dwordx4 v[190:191], v[244:247], off offset:128
	global_store_dwordx4 v[190:191], v[248:251], off offset:192
	s_mov_b64 s[56:57], 0xb0000
	s_mov_b64 s[6:7], 0

; #define GAS __attribute__((address_space(1)))
;     DI void operator()(const f32x4 (&acc)[2][2][4][2], const Unit& u, int wr, int wc, int fr, int fq) const {
;     ...
;             const int col0 = u.pn * BM + wc * 64 + 8 * fq;
;             f32x4 bb[2][2];
; #pragma unroll
;             for (int bj = 0; bj < 2; ++bj) { bb[bj][0] = *(const GAS f32x4*)(bias + col0 + bj * 32); bb[bj][1] = *(const GAS f32x4*)(bias + col0 + bj * 32 + 4); }
; #pragma unroll
;             for (int ai = 0; ai < 2; ++ai)
; #pragma unroll
;                 for (int m = 0; m < 4; ++m) { const size_t offb = (size_t)(row0 + ai * HALF + m * 16) * DM + col0;
;                     u32x4 brv[2], mgv[2];
; #pragma unroll
;                     for (int bj = 0; bj < 2; ++bj) { brv[bj] = *(const GAS u32x4*)(BR + offb + bj * 32); mgv[bj] = (gi > 0) ? *(const GAS u32x4*)(MG + offb + bj * 32) : (u32x4){0, 0, 0, 0}; }
.LBB0_812:
	v_readfirstlane_b32 s80, v148
	v_readfirstlane_b32 s81, v149
	v_readfirstlane_b32 s44, v150
	v_readfirstlane_b32 s45, v151
	v_readfirstlane_b32 s34, v152
	v_readfirstlane_b32 s35, v153
	v_readfirstlane_b32 s46, v134
	v_ashrrev_i32_e32 v177, 31, v176
	v_mov_b32_e32 v130, s80
	v_mov_b32_e32 v131, s81
	v_ashrrev_i32_e32 v179, 31, v178
	v_lshlrev_b64 v[146:147], 10, v[176:177]
	v_lshl_add_u64 v[134:135], v[178:179], 2, v[130:131]
	v_lshl_add_u64 v[164:165], v[146:147], 0, v[178:179]
	global_load_dwordx4 v[138:141], v[134:135], off offset:16
	global_load_dwordx4 v[142:145], v[134:135], off
	global_load_dwordx4 v[130:133], v[134:135], off offset:144
	s_nop 0
	global_load_dwordx4 v[134:137], v[134:135], off offset:128
	v_lshlrev_b64 v[148:149], 1, v[164:165]
	v_lshl_add_u64 v[146:147], s[44:45], 0, v[148:149]
	global_load_dwordx4 v[156:159], v[146:147], off
	s_cmp_gt_i32 s46, 0
	s_cselect_b64 s[0:1], -1, 0
	s_cmp_lt_i32 s46, 1
	v_lshl_add_u64 v[180:181], s[34:35], 0, v[148:149]
	s_cbranch_scc1 .LBB0_814
	global_load_dwordx4 v[160:163], v[180:181], off
	s_branch .LBB0_815
